# q up-projection epilogue: rope partner exchange via DPP row_ror:8 instead of 64 serialized LDS bpermutes per tile; attention cross-half row max via v_permlane32_swap
# baseline (speedup 1.0000x reference)
.Lsa_nold:
	v_add_co_u32_e32 v240, vcc, v240, v160
	v_addc_co_u32_e32 v241, vcc, 0, v241, vcc
	v_add_co_u32_e32 v242, vcc, v242, v161
	v_addc_co_u32_e32 v243, vcc, 0, v243, vcc
	v_cndmask_b32_e64 v160, v238, v239, s[44:45]
	v_mfma_f32_32x32x16_bf16 v[32:47], v[210:213], v[64:67], v[32:47]
	v_mfma_f32_32x32x16_bf16 v[48:63], v[234:237], v[64:67], v[48:63]
	v_add_co_u32_e32 v244, vcc, v244, v160
	v_addc_co_u32_e32 v245, vcc, 0, v245, vcc
	v_add_co_u32_e32 v246, vcc, 0x80, v246
	v_addc_co_u32_e32 v247, vcc, 0, v247, vcc
	v_add_co_u32_e32 v248, vcc, 0x80, v248
	v_addc_co_u32_e32 v249, vcc, 0, v249, vcc
	s_setprio 0
	s_nop 10
	v_max_f32_e32 v121, v48, v48
	v_max_f32_e32 v159, v32, v32
	v_max_f32_e32 v121, v159, v121
	v_max3_f32 v121, v121, v33, v49
	v_max3_f32 v121, v121, v34, v50
	v_max3_f32 v121, v121, v35, v51
	v_max3_f32 v121, v121, v36, v52
	v_max3_f32 v121, v121, v37, v53
	v_max3_f32 v121, v121, v38, v54
	v_max3_f32 v121, v121, v39, v55
	v_max3_f32 v121, v121, v40, v56
	v_max3_f32 v121, v121, v41, v57
	v_max3_f32 v121, v121, v42, v58
	v_max3_f32 v121, v121, v43, v59
	v_max3_f32 v121, v121, v44, v60
	v_max3_f32 v121, v121, v45, v61
	v_max3_f32 v121, v121, v46, v62
	v_cmp_lt_i32_e32 vcc, v177, v176
	v_max3_f32 v159, v121, v47, v63
	s_nop 0
	v_cndmask_b32_e32 v121, v175, v177, vcc
	v_lshlrev_b32_e32 v121, 2, v121
	v_mov_b32_e32 v160, v159
	s_nop 1
	v_permlane32_swap_b32 v160, v159
	v_max_f32_e32 v159, v159, v160
	v_add_f32_e32 v160, 0x41000000, v151
	v_cmp_gt_f32_e32 vcc, v159, v160
	s_cbranch_vccz .LBB0_381
	v_max_f32_e32 v159, v159, v159
	v_max_f32_e32 v160, v151, v151
	v_max_f32_e32 v159, v160, v159
	v_sub_f32_e32 v151, v151, v159
	v_exp_f32_e32 v160, v151
	v_mov_b32_e32 v151, v159
	v_pk_mul_f32 v[30:31], v[30:31], v[160:161] op_sel_hi:[1,0]
	v_pk_mul_f32 v[28:29], v[28:29], v[160:161] op_sel_hi:[1,0]
	v_pk_mul_f32 v[26:27], v[26:27], v[160:161] op_sel_hi:[1,0]
	v_pk_mul_f32 v[24:25], v[24:25], v[160:161] op_sel_hi:[1,0]
	v_pk_mul_f32 v[22:23], v[22:23], v[160:161] op_sel_hi:[1,0]
	v_pk_mul_f32 v[20:21], v[20:21], v[160:161] op_sel_hi:[1,0]
	v_pk_mul_f32 v[18:19], v[18:19], v[160:161] op_sel_hi:[1,0]
	v_pk_mul_f32 v[16:17], v[16:17], v[160:161] op_sel_hi:[1,0]
	v_pk_mul_f32 v[14:15], v[14:15], v[160:161] op_sel_hi:[1,0]
	v_pk_mul_f32 v[12:13], v[12:13], v[160:161] op_sel_hi:[1,0]
	v_pk_mul_f32 v[10:11], v[10:11], v[160:161] op_sel_hi:[1,0]
	v_pk_mul_f32 v[8:9], v[8:9], v[160:161] op_sel_hi:[1,0]
	v_pk_mul_f32 v[6:7], v[6:7], v[160:161] op_sel_hi:[1,0]
	v_pk_mul_f32 v[4:5], v[4:5], v[160:161] op_sel_hi:[1,0]
	v_pk_mul_f32 v[2:3], v[2:3], v[160:161] op_sel_hi:[1,0]
	v_pk_mul_f32 v[0:1], v[0:1], v[160:161] op_sel_hi:[1,0]
	v_mul_f32_e32 v119, v119, v160

.LBB0_727:
	s_or_b64 exec, exec, s[2:3]
	v_readlane_b32 s2, v252, 59
	v_lshlrev_b32_e32 v136, 1, v145
	v_readlane_b32 s3, v252, 60
	v_ashrrev_i32_e32 v111, 31, v110
	v_cmp_lt_i32_e32 vcc, v179, v176
	v_lshl_add_u64 v[98:99], s[2:3], 0, v[136:137]
	v_lshl_add_u64 v[134:135], v[110:111], 1, v[98:99]
	v_lshlrev_b32_sdwa v98, v250, sext(v97) dst_sel:DWORD dst_unused:UNUSED_PAD src0_sel:DWORD src1_sel:BYTE_0
	v_ashrrev_i32_e32 v99, 31, v98
	v_cndmask_b32_e32 v100, v175, v179, vcc
	v_lshl_add_u64 v[98:99], v[98:99], 1, s[46:47]
	v_lshlrev_b32_e32 v144, 2, v100
	v_lshl_add_u64 v[132:133], v[98:99], 0, v[136:137]
	v_mul_f32_e32 v98, 0x3e16c740, v80
	s_nop 1
	v_mov_b32_dpp v99, v98 row_ror:8 row_mask:0xf bank_mask:0xf
	s_movk_i32 s15, 0x600
	v_cvt_pk_bf16_f32 v80, v98, s0
	v_mad_i64_i32 v[104:105], s[2:3], v96, s15, v[134:135]
	v_ashrrev_i32_e32 v97, 31, v96
	global_store_short v[104:105], v80, off
	s_and_saveexec_b64 s[2:3], s[0:1]
	s_cbranch_execz .LBB0_729
	s_waitcnt vmcnt(32)
	v_mov_b32_e32 v100, v32
	s_waitcnt vmcnt(31)
	v_mov_b32_e32 v101, v16
	s_waitcnt lgkmcnt(0)
	v_pk_mul_f32 v[98:99], v[98:99], v[100:101]
	s_nop 0
	v_add_f32_e32 v80, v98, v99
	v_lshlrev_b64 v[98:99], 9, v[96:97]
	v_lshl_add_u64 v[98:99], v[132:133], 0, v[98:99]
	v_add_co_u32_e32 v98, vcc, 0xffc00000, v98
	v_cvt_pk_bf16_f32 v80, v80, s0
	s_nop 0
	v_addc_co_u32_e32 v99, vcc, -1, v99, vcc
	global_store_short v[98:99], v80, off
.LBB0_729:
	s_or_b64 exec, exec, s[2:3]
	v_or_b32_e32 v111, 1, v96
	v_mul_f32_e32 v80, 0x3e16c740, v81
	v_cvt_pk_bf16_f32 v81, v80, s0
	s_waitcnt lgkmcnt(0)
	v_mad_i64_i32 v[98:99], s[2:3], v111, s15, v[134:135]
	global_store_short v[98:99], v81, off
	s_nop 1
	v_mov_b32_dpp v81, v80 row_ror:8 row_mask:0xf bank_mask:0xf
	s_and_saveexec_b64 s[2:3], s[0:1]
	v_readlane_b32 s14, v252, 28
	s_cbranch_execz .LBB0_731
	s_waitcnt vmcnt(31)
	v_mov_b32_e32 v100, v33
	s_waitcnt vmcnt(30)
	v_mov_b32_e32 v101, v17
	s_waitcnt lgkmcnt(0)
	v_pk_mul_f32 v[80:81], v[80:81], v[100:101]
	s_nop 0
	v_add_f32_e32 v80, v80, v81
	v_cvt_pk_bf16_f32 v100, v80, s0
	v_lshlrev_b64 v[80:81], 9, v[96:97]
	v_lshl_add_u64 v[80:81], v[132:133], 0, v[80:81]
	v_add_co_u32_e32 v80, vcc, 0xffc01000, v80
	s_nop 1
	v_addc_co_u32_e32 v81, vcc, -1, v81, vcc
	global_store_short v[80:81], v100, off offset:-3584
.LBB0_731:
	s_or_b64 exec, exec, s[2:3]
	v_or_b32_e32 v148, 2, v96
	v_mul_f32_e32 v80, 0x3e16c740, v82
	s_waitcnt lgkmcnt(0)
	v_cvt_pk_bf16_f32 v81, v80, s0
	v_mad_i64_i32 v[100:101], s[2:3], v148, s15, v[134:135]
	global_store_short v[100:101], v81, off
	s_nop 1
	v_mov_b32_dpp v81, v80 row_ror:8 row_mask:0xf bank_mask:0xf
	s_and_saveexec_b64 s[2:3], s[0:1]
	s_cbranch_execz .LBB0_733
	s_waitcnt vmcnt(30)
	v_mov_b32_e32 v102, v34
	s_waitcnt vmcnt(29)
	v_mov_b32_e32 v103, v18
	s_waitcnt lgkmcnt(0)
	v_pk_mul_f32 v[80:81], v[80:81], v[102:103]
	s_nop 0
	v_add_f32_e32 v80, v80, v81
	v_cvt_pk_bf16_f32 v82, v80, s0
	v_lshlrev_b64 v[80:81], 9, v[96:97]
	v_lshl_add_u64 v[80:81], v[132:133], 0, v[80:81]
	v_add_co_u32_e32 v80, vcc, 0xffc01000, v80
	s_nop 1
	v_addc_co_u32_e32 v81, vcc, -1, v81, vcc
	global_store_short v[80:81], v82, off offset:-3072
.LBB0_733:
	s_or_b64 exec, exec, s[2:3]
	v_or_b32_e32 v150, 3, v96
	v_mul_f32_e32 v80, 0x3e16c740, v83
	s_waitcnt lgkmcnt(0)
	v_cvt_pk_bf16_f32 v81, v80, s0
	v_mad_i64_i32 v[102:103], s[2:3], v150, s15, v[134:135]
	global_store_short v[102:103], v81, off
	s_nop 1
	v_mov_b32_dpp v81, v80 row_ror:8 row_mask:0xf bank_mask:0xf
	s_and_saveexec_b64 s[2:3], s[0:1]
	s_cbranch_execz .LBB0_735
	s_waitcnt vmcnt(29)
	v_mov_b32_e32 v82, v35
	s_waitcnt vmcnt(28)
	v_mov_b32_e32 v83, v19
	s_waitcnt lgkmcnt(0)
	v_pk_mul_f32 v[80:81], v[80:81], v[82:83]
	s_nop 0
	v_add_f32_e32 v80, v80, v81
	v_cvt_pk_bf16_f32 v82, v80, s0
	v_lshlrev_b64 v[80:81], 9, v[96:97]
	v_lshl_add_u64 v[80:81], v[132:133], 0, v[80:81]
	v_add_co_u32_e32 v80, vcc, 0xffc01000, v80
	s_nop 1
	v_addc_co_u32_e32 v81, vcc, -1, v81, vcc
	global_store_short v[80:81], v82, off offset:-2560
.LBB0_735:
	s_or_b64 exec, exec, s[2:3]
	v_or_b32_e32 v152, 8, v96
	v_mul_f32_e32 v80, 0x3e16c740, v84
	s_waitcnt lgkmcnt(0)
	v_cvt_pk_bf16_f32 v81, v80, s0
	v_mad_i64_i32 v[106:107], s[2:3], v152, s15, v[134:135]
	global_store_short v[106:107], v81, off
	s_nop 1
	v_mov_b32_dpp v81, v80 row_ror:8 row_mask:0xf bank_mask:0xf
	s_and_saveexec_b64 s[2:3], s[0:1]
	s_cbranch_execz .LBB0_737
	s_waitcnt vmcnt(28)
	v_mov_b32_e32 v82, v36
	s_waitcnt vmcnt(27)
	v_mov_b32_e32 v83, v20
	s_waitcnt lgkmcnt(0)
	v_pk_mul_f32 v[80:81], v[80:81], v[82:83]
	s_nop 0
	v_add_f32_e32 v80, v80, v81
	v_cvt_pk_bf16_f32 v82, v80, s0
	v_lshlrev_b64 v[80:81], 9, v[96:97]
	v_lshl_add_u64 v[80:81], v[132:133], 0, v[80:81]
	v_add_co_u32_e32 v80, vcc, 0xffc01000, v80
	s_nop 1
	v_addc_co_u32_e32 v81, vcc, -1, v81, vcc
	global_store_short v[80:81], v82, off
.LBB0_737:
	s_or_b64 exec, exec, s[2:3]
	v_or_b32_e32 v155, 9, v96
	v_mul_f32_e32 v80, 0x3e16c740, v85
	s_waitcnt lgkmcnt(0)
	v_cvt_pk_bf16_f32 v81, v80, s0
	v_mad_i64_i32 v[108:109], s[2:3], v155, s15, v[134:135]
	global_store_short v[108:109], v81, off
	s_nop 1
	v_mov_b32_dpp v81, v80 row_ror:8 row_mask:0xf bank_mask:0xf
	s_and_saveexec_b64 s[2:3], s[0:1]
	s_cbranch_execz .LBB0_739
	s_waitcnt vmcnt(27)
	v_mov_b32_e32 v82, v37
	s_waitcnt vmcnt(26)
	v_mov_b32_e32 v83, v21
	s_waitcnt lgkmcnt(0)
	v_pk_mul_f32 v[80:81], v[80:81], v[82:83]
	s_nop 0
	v_add_f32_e32 v80, v80, v81
	v_cvt_pk_bf16_f32 v82, v80, s0
	v_lshlrev_b64 v[80:81], 9, v[96:97]
	v_lshl_add_u64 v[80:81], v[132:133], 0, v[80:81]
	v_add_co_u32_e32 v80, vcc, 0xffc02000, v80
	s_nop 1
	v_addc_co_u32_e32 v81, vcc, -1, v81, vcc
	global_store_short v[80:81], v82, off offset:-3584
.LBB0_739:
	s_or_b64 exec, exec, s[2:3]
	v_or_b32_e32 v157, 10, v96
	v_mul_f32_e32 v80, 0x3e16c740, v86
	s_waitcnt lgkmcnt(0)
	v_cvt_pk_bf16_f32 v81, v80, s0
	v_mad_i64_i32 v[112:113], s[2:3], v157, s15, v[134:135]
	global_store_short v[112:113], v81, off
	s_nop 1
	v_mov_b32_dpp v81, v80 row_ror:8 row_mask:0xf bank_mask:0xf
	s_and_saveexec_b64 s[2:3], s[0:1]
	s_cbranch_execz .LBB0_741
	s_waitcnt vmcnt(26)
	v_mov_b32_e32 v82, v38
	s_waitcnt vmcnt(25)
	v_mov_b32_e32 v83, v22
	s_waitcnt lgkmcnt(0)
	v_pk_mul_f32 v[80:81], v[80:81], v[82:83]
	s_nop 0
	v_add_f32_e32 v80, v80, v81
	v_cvt_pk_bf16_f32 v82, v80, s0
	v_lshlrev_b64 v[80:81], 9, v[96:97]
	v_lshl_add_u64 v[80:81], v[132:133], 0, v[80:81]
	v_add_co_u32_e32 v80, vcc, 0xffc02000, v80
	s_nop 1
	v_addc_co_u32_e32 v81, vcc, -1, v81, vcc
	global_store_short v[80:81], v82, off offset:-3072
.LBB0_741:
	s_or_b64 exec, exec, s[2:3]
	v_or_b32_e32 v159, 11, v96
	v_mul_f32_e32 v80, 0x3e16c740, v87
	s_waitcnt lgkmcnt(0)
	v_cvt_pk_bf16_f32 v81, v80, s0
	v_mad_i64_i32 v[114:115], s[2:3], v159, s15, v[134:135]
	global_store_short v[114:115], v81, off
	s_nop 1
	v_mov_b32_dpp v81, v80 row_ror:8 row_mask:0xf bank_mask:0xf
	s_and_saveexec_b64 s[2:3], s[0:1]
	s_cbranch_execz .LBB0_743
	s_waitcnt vmcnt(25)
	v_mov_b32_e32 v82, v39
	s_waitcnt vmcnt(24)
	v_mov_b32_e32 v83, v23
	s_waitcnt lgkmcnt(0)
	v_pk_mul_f32 v[80:81], v[80:81], v[82:83]
	s_nop 0
	v_add_f32_e32 v80, v80, v81
	v_cvt_pk_bf16_f32 v82, v80, s0
	v_lshlrev_b64 v[80:81], 9, v[96:97]
	v_lshl_add_u64 v[80:81], v[132:133], 0, v[80:81]
	v_add_co_u32_e32 v80, vcc, 0xffc02000, v80
	s_nop 1
	v_addc_co_u32_e32 v81, vcc, -1, v81, vcc
	global_store_short v[80:81], v82, off offset:-2560
.LBB0_743:
	s_or_b64 exec, exec, s[2:3]
	v_or_b32_e32 v161, 16, v96
	v_mul_f32_e32 v80, 0x3e16c740, v88
	s_waitcnt lgkmcnt(0)
	v_cvt_pk_bf16_f32 v81, v80, s0
	v_mad_i64_i32 v[116:117], s[2:3], v161, s15, v[134:135]
	global_store_short v[116:117], v81, off
	s_nop 1
	v_mov_b32_dpp v81, v80 row_ror:8 row_mask:0xf bank_mask:0xf
	s_and_saveexec_b64 s[2:3], s[0:1]
	s_cbranch_execz .LBB0_745
	s_waitcnt vmcnt(24)
	v_mov_b32_e32 v82, v40
	s_waitcnt vmcnt(23)
	v_mov_b32_e32 v83, v24
	s_waitcnt lgkmcnt(0)
	v_pk_mul_f32 v[80:81], v[80:81], v[82:83]
	s_nop 0
	v_add_f32_e32 v80, v80, v81
	v_cvt_pk_bf16_f32 v82, v80, s0
	v_lshlrev_b64 v[80:81], 9, v[96:97]
	v_lshl_add_u64 v[80:81], v[132:133], 0, v[80:81]
	v_add_co_u32_e32 v80, vcc, 0xffc02000, v80
	s_nop 1
	v_addc_co_u32_e32 v81, vcc, -1, v81, vcc
	global_store_short v[80:81], v82, off
.LBB0_745:
	s_or_b64 exec, exec, s[2:3]
	v_or_b32_e32 v163, 17, v96
	v_mul_f32_e32 v80, 0x3e16c740, v89
	s_waitcnt lgkmcnt(0)
	v_cvt_pk_bf16_f32 v81, v80, s0
	v_mad_i64_i32 v[118:119], s[2:3], v163, s15, v[134:135]
	global_store_short v[118:119], v81, off
	s_nop 1
	v_mov_b32_dpp v81, v80 row_ror:8 row_mask:0xf bank_mask:0xf
	s_and_saveexec_b64 s[2:3], s[0:1]
	s_cbranch_execz .LBB0_747
	s_waitcnt vmcnt(23)
	v_mov_b32_e32 v82, v41
	s_waitcnt vmcnt(22)
	v_mov_b32_e32 v83, v25
	s_waitcnt lgkmcnt(0)
	v_pk_mul_f32 v[80:81], v[80:81], v[82:83]
	s_nop 0
	v_add_f32_e32 v80, v80, v81
	v_cvt_pk_bf16_f32 v82, v80, s0
	v_lshlrev_b64 v[80:81], 9, v[96:97]
	v_lshl_add_u64 v[80:81], v[132:133], 0, v[80:81]
	v_add_co_u32_e32 v80, vcc, 0xffc03000, v80
	s_nop 1
	v_addc_co_u32_e32 v81, vcc, -1, v81, vcc
	global_store_short v[80:81], v82, off offset:-3584
.LBB0_747:
	s_or_b64 exec, exec, s[2:3]
	v_or_b32_e32 v165, 18, v96
	v_mul_f32_e32 v80, 0x3e16c740, v90
	s_waitcnt lgkmcnt(0)
	v_cvt_pk_bf16_f32 v81, v80, s0
	v_mad_i64_i32 v[120:121], s[2:3], v165, s15, v[134:135]
	global_store_short v[120:121], v81, off
	s_nop 1
	v_mov_b32_dpp v81, v80 row_ror:8 row_mask:0xf bank_mask:0xf
	s_and_saveexec_b64 s[2:3], s[0:1]
	s_cbranch_execz .LBB0_749
	s_waitcnt vmcnt(22)
	v_mov_b32_e32 v82, v42
	s_waitcnt vmcnt(21)
	v_mov_b32_e32 v83, v26
	s_waitcnt lgkmcnt(0)
	v_pk_mul_f32 v[80:81], v[80:81], v[82:83]
	s_nop 0
	v_add_f32_e32 v80, v80, v81
	v_cvt_pk_bf16_f32 v82, v80, s0
	v_lshlrev_b64 v[80:81], 9, v[96:97]
	v_lshl_add_u64 v[80:81], v[132:133], 0, v[80:81]
	v_add_co_u32_e32 v80, vcc, 0xffc03000, v80
	s_nop 1
	v_addc_co_u32_e32 v81, vcc, -1, v81, vcc
	global_store_short v[80:81], v82, off offset:-3072
.LBB0_749:
	s_or_b64 exec, exec, s[2:3]
	v_or_b32_e32 v168, 19, v96
	v_mul_f32_e32 v80, 0x3e16c740, v91
	s_waitcnt lgkmcnt(0)
	v_cvt_pk_bf16_f32 v81, v80, s0
	v_mad_i64_i32 v[122:123], s[2:3], v168, s15, v[134:135]
	global_store_short v[122:123], v81, off
	s_nop 1
	v_mov_b32_dpp v81, v80 row_ror:8 row_mask:0xf bank_mask:0xf
	s_and_saveexec_b64 s[2:3], s[0:1]
	s_cbranch_execz .LBB0_751
	s_waitcnt vmcnt(21)
	v_mov_b32_e32 v82, v43
	s_waitcnt vmcnt(20)
	v_mov_b32_e32 v83, v27
	s_waitcnt lgkmcnt(0)
	v_pk_mul_f32 v[80:81], v[80:81], v[82:83]
	s_nop 0
	v_add_f32_e32 v80, v80, v81
	v_cvt_pk_bf16_f32 v82, v80, s0
	v_lshlrev_b64 v[80:81], 9, v[96:97]
	v_lshl_add_u64 v[80:81], v[132:133], 0, v[80:81]
	v_add_co_u32_e32 v80, vcc, 0xffc03000, v80
	s_nop 1
	v_addc_co_u32_e32 v81, vcc, -1, v81, vcc
	global_store_short v[80:81], v82, off offset:-2560
.LBB0_751:
	s_or_b64 exec, exec, s[2:3]
	v_or_b32_e32 v170, 24, v96
	v_mul_f32_e32 v80, 0x3e16c740, v92
	s_waitcnt lgkmcnt(0)
	v_cvt_pk_bf16_f32 v81, v80, s0
	v_mad_i64_i32 v[124:125], s[2:3], v170, s15, v[134:135]
	global_store_short v[124:125], v81, off
	s_nop 1
	v_mov_b32_dpp v81, v80 row_ror:8 row_mask:0xf bank_mask:0xf
	s_and_saveexec_b64 s[2:3], s[0:1]
	s_cbranch_execz .LBB0_753
	s_waitcnt vmcnt(20)
	v_mov_b32_e32 v82, v44
	s_waitcnt vmcnt(19)
	v_mov_b32_e32 v83, v28
	s_waitcnt lgkmcnt(0)
	v_pk_mul_f32 v[80:81], v[80:81], v[82:83]
	s_nop 0
	v_add_f32_e32 v80, v80, v81
	v_cvt_pk_bf16_f32 v82, v80, s0
	v_lshlrev_b64 v[80:81], 9, v[96:97]
	v_lshl_add_u64 v[80:81], v[132:133], 0, v[80:81]
	v_add_co_u32_e32 v80, vcc, 0xffc03000, v80
	s_nop 1
	v_addc_co_u32_e32 v81, vcc, -1, v81, vcc
	global_store_short v[80:81], v82, off
.LBB0_753:
	s_or_b64 exec, exec, s[2:3]
	v_or_b32_e32 v172, 25, v96
	v_mul_f32_e32 v80, 0x3e16c740, v93
	s_waitcnt lgkmcnt(0)
	v_cvt_pk_bf16_f32 v81, v80, s0
	v_mad_i64_i32 v[126:127], s[2:3], v172, s15, v[134:135]
	global_store_short v[126:127], v81, off
	s_nop 1
	v_mov_b32_dpp v81, v80 row_ror:8 row_mask:0xf bank_mask:0xf
	s_and_saveexec_b64 s[2:3], s[0:1]
	s_cbranch_execz .LBB0_755
	s_waitcnt vmcnt(19)
	v_mov_b32_e32 v82, v45
	s_waitcnt vmcnt(18)
	v_mov_b32_e32 v83, v29
	s_waitcnt lgkmcnt(0)
	v_pk_mul_f32 v[80:81], v[80:81], v[82:83]
	s_nop 0
	v_add_f32_e32 v80, v80, v81
	v_cvt_pk_bf16_f32 v82, v80, s0
	v_lshlrev_b64 v[80:81], 9, v[96:97]
	v_lshl_add_u64 v[80:81], v[132:133], 0, v[80:81]
	v_add_co_u32_e32 v80, vcc, 0xffc04000, v80
	s_nop 1
	v_addc_co_u32_e32 v81, vcc, -1, v81, vcc
	global_store_short v[80:81], v82, off offset:-3584
.LBB0_755:
	s_or_b64 exec, exec, s[2:3]
	v_or_b32_e32 v193, 26, v96
	v_mul_f32_e32 v80, 0x3e16c740, v94
	s_waitcnt lgkmcnt(0)
	v_cvt_pk_bf16_f32 v81, v80, s0
	v_mad_i64_i32 v[128:129], s[2:3], v193, s15, v[134:135]
	global_store_short v[128:129], v81, off
	s_nop 1
	v_mov_b32_dpp v81, v80 row_ror:8 row_mask:0xf bank_mask:0xf
	s_and_saveexec_b64 s[2:3], s[0:1]
	s_cbranch_execz .LBB0_757
	s_waitcnt vmcnt(18)
	v_mov_b32_e32 v82, v46
	s_waitcnt vmcnt(17)
	v_mov_b32_e32 v83, v30
	s_waitcnt lgkmcnt(0)
	v_pk_mul_f32 v[80:81], v[80:81], v[82:83]
	s_nop 0
	v_add_f32_e32 v80, v80, v81
	v_cvt_pk_bf16_f32 v82, v80, s0
	v_lshlrev_b64 v[80:81], 9, v[96:97]
	v_lshl_add_u64 v[80:81], v[132:133], 0, v[80:81]
	v_add_co_u32_e32 v80, vcc, 0xffc04000, v80
	s_nop 1
	v_addc_co_u32_e32 v81, vcc, -1, v81, vcc
	global_store_short v[80:81], v82, off offset:-3072
.LBB0_757:
	s_or_b64 exec, exec, s[2:3]
	v_or_b32_e32 v195, 27, v96
	v_mul_f32_e32 v80, 0x3e16c740, v95
	s_waitcnt lgkmcnt(0)
	v_cvt_pk_bf16_f32 v81, v80, s0
	v_mad_i64_i32 v[130:131], s[2:3], v195, s15, v[134:135]
	global_store_short v[130:131], v81, off
	s_nop 1
	v_mov_b32_dpp v81, v80 row_ror:8 row_mask:0xf bank_mask:0xf
	s_and_saveexec_b64 s[2:3], s[0:1]
	s_cbranch_execz .LBB0_759
	s_waitcnt vmcnt(17)
	v_mov_b32_e32 v82, v47
	s_waitcnt vmcnt(16)
	v_mov_b32_e32 v83, v31
	s_waitcnt lgkmcnt(0)
	v_pk_mul_f32 v[80:81], v[80:81], v[82:83]
	s_nop 0
	v_add_f32_e32 v80, v80, v81
	v_cvt_pk_bf16_f32 v82, v80, s0
	v_lshlrev_b64 v[80:81], 9, v[96:97]
	v_lshl_add_u64 v[80:81], v[132:133], 0, v[80:81]
	v_add_co_u32_e32 v80, vcc, 0xffc04000, v80
	s_nop 1
	v_addc_co_u32_e32 v81, vcc, -1, v81, vcc
	global_store_short v[80:81], v82, off offset:-2560

.LBB0_761:
	s_or_b64 exec, exec, s[2:3]
	v_mul_f32_e32 v82, 0x3e16c740, v64
	s_nop 1
	v_mov_b32_dpp v83, v82 row_ror:8 row_mask:0xf bank_mask:0xf
	v_cvt_pk_bf16_f32 v64, v82, s0
	v_mad_i64_i32 v[80:81], s[2:3], v80, s15, v[134:135]
	global_store_short v[80:81], v64, off
	s_and_saveexec_b64 s[2:3], s[0:1]
	s_cbranch_execz .LBB0_763
	s_waitcnt vmcnt(32)
	v_mov_b32_e32 v84, v32
	s_waitcnt vmcnt(31)
	v_mov_b32_e32 v85, v16
	s_waitcnt lgkmcnt(0)
	v_pk_mul_f32 v[82:83], v[82:83], v[84:85]
	s_nop 0
	v_add_f32_e32 v64, v82, v83
	v_lshlrev_b64 v[82:83], 9, v[96:97]
	v_lshl_add_u64 v[82:83], v[132:133], 0, v[82:83]
	v_add_co_u32_e32 v82, vcc, 0xffc04000, v82
	v_cvt_pk_bf16_f32 v64, v64, s0
	s_nop 0
	v_addc_co_u32_e32 v83, vcc, -1, v83, vcc
	global_store_short v[82:83], v64, off
.LBB0_763:
	s_or_b64 exec, exec, s[2:3]
	v_or_b32_e32 v149, 33, v96
	v_mul_f32_e32 v82, 0x3e16c740, v65
	s_waitcnt lgkmcnt(0)
	v_cvt_pk_bf16_f32 v83, v82, s0
	v_mad_i64_i32 v[64:65], s[2:3], v149, s15, v[134:135]
	global_store_short v[64:65], v83, off
	s_nop 1
	v_mov_b32_dpp v83, v82 row_ror:8 row_mask:0xf bank_mask:0xf
	s_and_saveexec_b64 s[2:3], s[0:1]
	s_cbranch_execz .LBB0_765
	s_waitcnt vmcnt(31)
	v_mov_b32_e32 v84, v33
	s_waitcnt vmcnt(30)
	v_mov_b32_e32 v85, v17
	s_waitcnt lgkmcnt(0)
	v_pk_mul_f32 v[82:83], v[82:83], v[84:85]
	s_nop 0
	v_add_f32_e32 v82, v82, v83
	v_cvt_pk_bf16_f32 v84, v82, s0
	v_lshlrev_b64 v[82:83], 9, v[96:97]
	v_lshl_add_u64 v[82:83], v[132:133], 0, v[82:83]
	v_add_co_u32_e32 v82, vcc, 0xffc05000, v82
	s_nop 1
	v_addc_co_u32_e32 v83, vcc, -1, v83, vcc
	global_store_short v[82:83], v84, off offset:-3584
.LBB0_765:
	s_or_b64 exec, exec, s[2:3]
	v_mul_f32_e32 v84, 0x3e16c740, v66
	s_nop 1
	v_mov_b32_dpp v85, v84 row_ror:8 row_mask:0xf bank_mask:0xf
	v_or_b32_e32 v151, 34, v96
	v_cvt_pk_bf16_f32 v66, v84, s0
	s_waitcnt lgkmcnt(1)
	v_mad_i64_i32 v[82:83], s[2:3], v151, s15, v[134:135]
	global_store_short v[82:83], v66, off
	s_and_saveexec_b64 s[2:3], s[0:1]
	s_cbranch_execz .LBB0_767
	s_waitcnt vmcnt(30)
	v_mov_b32_e32 v86, v34
	s_waitcnt vmcnt(29)
	v_mov_b32_e32 v87, v18
	s_waitcnt lgkmcnt(0)
	v_pk_mul_f32 v[84:85], v[84:85], v[86:87]
	s_nop 0
	v_add_f32_e32 v66, v84, v85
	v_lshlrev_b64 v[84:85], 9, v[96:97]
	v_lshl_add_u64 v[84:85], v[132:133], 0, v[84:85]
	v_add_co_u32_e32 v84, vcc, 0xffc05000, v84
	v_cvt_pk_bf16_f32 v66, v66, s0
	s_nop 0
	v_addc_co_u32_e32 v85, vcc, -1, v85, vcc
	global_store_short v[84:85], v66, off offset:-3072
.LBB0_767:
	s_or_b64 exec, exec, s[2:3]
	v_or_b32_e32 v153, 35, v96
	v_mul_f32_e32 v84, 0x3e16c740, v67
	s_waitcnt lgkmcnt(0)
	v_cvt_pk_bf16_f32 v85, v84, s0
	v_mad_i64_i32 v[66:67], s[2:3], v153, s15, v[134:135]
	global_store_short v[66:67], v85, off
	s_nop 1
	v_mov_b32_dpp v85, v84 row_ror:8 row_mask:0xf bank_mask:0xf
	s_and_saveexec_b64 s[2:3], s[0:1]
	s_cbranch_execz .LBB0_769
	s_waitcnt vmcnt(29)
	v_mov_b32_e32 v86, v35
	s_waitcnt vmcnt(28)
	v_mov_b32_e32 v87, v19
	s_waitcnt lgkmcnt(0)
	v_pk_mul_f32 v[84:85], v[84:85], v[86:87]
	s_nop 0
	v_add_f32_e32 v84, v84, v85
	v_cvt_pk_bf16_f32 v86, v84, s0
	v_lshlrev_b64 v[84:85], 9, v[96:97]
	v_lshl_add_u64 v[84:85], v[132:133], 0, v[84:85]
	v_add_co_u32_e32 v84, vcc, 0xffc05000, v84
	s_nop 1
	v_addc_co_u32_e32 v85, vcc, -1, v85, vcc
	global_store_short v[84:85], v86, off offset:-2560
.LBB0_769:
	s_or_b64 exec, exec, s[2:3]
	v_mul_f32_e32 v86, 0x3e16c740, v68
	s_nop 1
	v_mov_b32_dpp v87, v86 row_ror:8 row_mask:0xf bank_mask:0xf
	v_or_b32_e32 v154, 40, v96
	v_cvt_pk_bf16_f32 v68, v86, s0
	s_waitcnt lgkmcnt(1)
	v_mad_i64_i32 v[84:85], s[2:3], v154, s15, v[134:135]
	global_store_short v[84:85], v68, off
	s_and_saveexec_b64 s[2:3], s[0:1]
	s_cbranch_execz .LBB0_771
	s_waitcnt vmcnt(28)
	v_mov_b32_e32 v88, v36
	s_waitcnt vmcnt(27)
	v_mov_b32_e32 v89, v20
	s_waitcnt lgkmcnt(0)
	v_pk_mul_f32 v[86:87], v[86:87], v[88:89]
	s_nop 0
	v_add_f32_e32 v68, v86, v87
	v_lshlrev_b64 v[86:87], 9, v[96:97]
	v_lshl_add_u64 v[86:87], v[132:133], 0, v[86:87]
	v_add_co_u32_e32 v86, vcc, 0xffc05000, v86
	v_cvt_pk_bf16_f32 v68, v68, s0
	s_nop 0
	v_addc_co_u32_e32 v87, vcc, -1, v87, vcc
	global_store_short v[86:87], v68, off
.LBB0_771:
	s_or_b64 exec, exec, s[2:3]
	v_or_b32_e32 v156, 41, v96
	v_mul_f32_e32 v86, 0x3e16c740, v69
	s_waitcnt lgkmcnt(0)
	v_cvt_pk_bf16_f32 v87, v86, s0
	v_mad_i64_i32 v[68:69], s[2:3], v156, s15, v[134:135]
	global_store_short v[68:69], v87, off
	s_nop 1
	v_mov_b32_dpp v87, v86 row_ror:8 row_mask:0xf bank_mask:0xf
	s_and_saveexec_b64 s[2:3], s[0:1]
	s_cbranch_execz .LBB0_773
	s_waitcnt vmcnt(27)
	v_mov_b32_e32 v88, v37
	s_waitcnt vmcnt(26)
	v_mov_b32_e32 v89, v21
	s_waitcnt lgkmcnt(0)
	v_pk_mul_f32 v[86:87], v[86:87], v[88:89]
	s_nop 0
	v_add_f32_e32 v86, v86, v87
	v_cvt_pk_bf16_f32 v88, v86, s0
	v_lshlrev_b64 v[86:87], 9, v[96:97]
	v_lshl_add_u64 v[86:87], v[132:133], 0, v[86:87]
	v_add_co_u32_e32 v86, vcc, 0xffc06000, v86
	s_nop 1
	v_addc_co_u32_e32 v87, vcc, -1, v87, vcc
	global_store_short v[86:87], v88, off offset:-3584
.LBB0_773:
	s_or_b64 exec, exec, s[2:3]
	v_mul_f32_e32 v88, 0x3e16c740, v70
	s_nop 1
	v_mov_b32_dpp v89, v88 row_ror:8 row_mask:0xf bank_mask:0xf
	v_or_b32_e32 v158, 42, v96
	v_cvt_pk_bf16_f32 v70, v88, s0
	s_waitcnt lgkmcnt(1)
	v_mad_i64_i32 v[86:87], s[2:3], v158, s15, v[134:135]
	global_store_short v[86:87], v70, off
	s_and_saveexec_b64 s[2:3], s[0:1]
	s_cbranch_execz .LBB0_775
	s_waitcnt vmcnt(26)
	v_mov_b32_e32 v90, v38
	s_waitcnt vmcnt(25)
	v_mov_b32_e32 v91, v22
	s_waitcnt lgkmcnt(0)
	v_pk_mul_f32 v[88:89], v[88:89], v[90:91]
	s_nop 0
	v_add_f32_e32 v70, v88, v89
	v_lshlrev_b64 v[88:89], 9, v[96:97]
	v_lshl_add_u64 v[88:89], v[132:133], 0, v[88:89]
	v_add_co_u32_e32 v88, vcc, 0xffc06000, v88
	v_cvt_pk_bf16_f32 v70, v70, s0
	s_nop 0
	v_addc_co_u32_e32 v89, vcc, -1, v89, vcc
	global_store_short v[88:89], v70, off offset:-3072
.LBB0_775:
	s_or_b64 exec, exec, s[2:3]
	v_or_b32_e32 v160, 43, v96
	v_mul_f32_e32 v88, 0x3e16c740, v71
	s_waitcnt lgkmcnt(0)
	v_cvt_pk_bf16_f32 v89, v88, s0
	v_mad_i64_i32 v[70:71], s[2:3], v160, s15, v[134:135]
	global_store_short v[70:71], v89, off
	s_nop 1
	v_mov_b32_dpp v89, v88 row_ror:8 row_mask:0xf bank_mask:0xf
	s_and_saveexec_b64 s[2:3], s[0:1]
	s_cbranch_execz .LBB0_777
	s_waitcnt vmcnt(25)
	v_mov_b32_e32 v90, v39
	s_waitcnt vmcnt(24)
	v_mov_b32_e32 v91, v23
	s_waitcnt lgkmcnt(0)
	v_pk_mul_f32 v[88:89], v[88:89], v[90:91]
	s_nop 0
	v_add_f32_e32 v88, v88, v89
	v_cvt_pk_bf16_f32 v90, v88, s0
	v_lshlrev_b64 v[88:89], 9, v[96:97]
	v_lshl_add_u64 v[88:89], v[132:133], 0, v[88:89]
	v_add_co_u32_e32 v88, vcc, 0xffc06000, v88
	s_nop 1
	v_addc_co_u32_e32 v89, vcc, -1, v89, vcc
	global_store_short v[88:89], v90, off offset:-2560
.LBB0_777:
	s_or_b64 exec, exec, s[2:3]
	v_mul_f32_e32 v90, 0x3e16c740, v72
	s_nop 1
	v_mov_b32_dpp v91, v90 row_ror:8 row_mask:0xf bank_mask:0xf
	v_or_b32_e32 v162, 48, v96
	v_cvt_pk_bf16_f32 v72, v90, s0
	s_waitcnt lgkmcnt(1)
	v_mad_i64_i32 v[88:89], s[2:3], v162, s15, v[134:135]
	global_store_short v[88:89], v72, off
	s_and_saveexec_b64 s[2:3], s[0:1]
	s_cbranch_execz .LBB0_779
	s_waitcnt vmcnt(24)
	v_mov_b32_e32 v92, v40
	s_waitcnt vmcnt(23)
	v_mov_b32_e32 v93, v24
	s_waitcnt lgkmcnt(0)
	v_pk_mul_f32 v[90:91], v[90:91], v[92:93]
	s_nop 0
	v_add_f32_e32 v72, v90, v91
	v_lshlrev_b64 v[90:91], 9, v[96:97]
	v_lshl_add_u64 v[90:91], v[132:133], 0, v[90:91]
	v_add_co_u32_e32 v90, vcc, 0xffc06000, v90
	v_cvt_pk_bf16_f32 v72, v72, s0
	s_nop 0
	v_addc_co_u32_e32 v91, vcc, -1, v91, vcc
	global_store_short v[90:91], v72, off
.LBB0_779:
	s_or_b64 exec, exec, s[2:3]
	v_or_b32_e32 v164, 49, v96
	v_mul_f32_e32 v90, 0x3e16c740, v73
	s_waitcnt lgkmcnt(0)
	v_cvt_pk_bf16_f32 v91, v90, s0
	v_mad_i64_i32 v[72:73], s[2:3], v164, s15, v[134:135]
	global_store_short v[72:73], v91, off
	s_nop 1
	v_mov_b32_dpp v91, v90 row_ror:8 row_mask:0xf bank_mask:0xf
	s_and_saveexec_b64 s[2:3], s[0:1]
	s_cbranch_execz .LBB0_781
	s_waitcnt vmcnt(23)
	v_mov_b32_e32 v92, v41
	s_waitcnt vmcnt(22)
	v_mov_b32_e32 v93, v25
	s_waitcnt lgkmcnt(0)
	v_pk_mul_f32 v[90:91], v[90:91], v[92:93]
	s_nop 0
	v_add_f32_e32 v90, v90, v91
	v_cvt_pk_bf16_f32 v92, v90, s0
	v_lshlrev_b64 v[90:91], 9, v[96:97]
	v_lshl_add_u64 v[90:91], v[132:133], 0, v[90:91]
	v_add_co_u32_e32 v90, vcc, 0xffc07000, v90
	s_nop 1
	v_addc_co_u32_e32 v91, vcc, -1, v91, vcc
	global_store_short v[90:91], v92, off offset:-3584
.LBB0_781:
	s_or_b64 exec, exec, s[2:3]
	v_mul_f32_e32 v92, 0x3e16c740, v74
	s_nop 1
	v_mov_b32_dpp v93, v92 row_ror:8 row_mask:0xf bank_mask:0xf
	v_or_b32_e32 v166, 50, v96
	v_cvt_pk_bf16_f32 v74, v92, s0
	s_waitcnt lgkmcnt(1)
	v_mad_i64_i32 v[90:91], s[2:3], v166, s15, v[134:135]
	global_store_short v[90:91], v74, off
	s_and_saveexec_b64 s[2:3], s[0:1]
	s_cbranch_execz .LBB0_783
	s_waitcnt vmcnt(22)
	v_mov_b32_e32 v94, v42
	s_waitcnt vmcnt(21)
	v_mov_b32_e32 v95, v26
	s_waitcnt lgkmcnt(0)
	v_pk_mul_f32 v[92:93], v[92:93], v[94:95]
	s_nop 0
	v_add_f32_e32 v74, v92, v93
	v_lshlrev_b64 v[92:93], 9, v[96:97]
	v_lshl_add_u64 v[92:93], v[132:133], 0, v[92:93]
	v_add_co_u32_e32 v92, vcc, 0xffc07000, v92
	v_cvt_pk_bf16_f32 v74, v74, s0
	s_nop 0
	v_addc_co_u32_e32 v93, vcc, -1, v93, vcc
	global_store_short v[92:93], v74, off offset:-3072
.LBB0_783:
	s_or_b64 exec, exec, s[2:3]
	v_or_b32_e32 v167, 51, v96
	v_mul_f32_e32 v92, 0x3e16c740, v75
	s_waitcnt lgkmcnt(0)
	v_cvt_pk_bf16_f32 v93, v92, s0
	v_mad_i64_i32 v[74:75], s[2:3], v167, s15, v[134:135]
	global_store_short v[74:75], v93, off
	s_nop 1
	v_mov_b32_dpp v93, v92 row_ror:8 row_mask:0xf bank_mask:0xf
	s_and_saveexec_b64 s[2:3], s[0:1]
	s_cbranch_execz .LBB0_785
	s_waitcnt vmcnt(21)
	v_mov_b32_e32 v94, v43
	s_waitcnt vmcnt(20)
	v_mov_b32_e32 v95, v27
	s_waitcnt lgkmcnt(0)
	v_pk_mul_f32 v[92:93], v[92:93], v[94:95]
	s_nop 0
	v_add_f32_e32 v92, v92, v93
	v_cvt_pk_bf16_f32 v94, v92, s0
	v_lshlrev_b64 v[92:93], 9, v[96:97]
	v_lshl_add_u64 v[92:93], v[132:133], 0, v[92:93]
	v_add_co_u32_e32 v92, vcc, 0xffc07000, v92
	s_nop 1
	v_addc_co_u32_e32 v93, vcc, -1, v93, vcc
	global_store_short v[92:93], v94, off offset:-2560
.LBB0_785:
	s_or_b64 exec, exec, s[2:3]
	v_mul_f32_e32 v94, 0x3e16c740, v76
	s_nop 1
	v_mov_b32_dpp v95, v94 row_ror:8 row_mask:0xf bank_mask:0xf
	v_or_b32_e32 v169, 56, v96
	v_cvt_pk_bf16_f32 v76, v94, s0
	s_waitcnt lgkmcnt(1)
	v_mad_i64_i32 v[92:93], s[2:3], v169, s15, v[134:135]
	global_store_short v[92:93], v76, off
	s_and_saveexec_b64 s[2:3], s[0:1]
	s_cbranch_execz .LBB0_787
	s_waitcnt vmcnt(20)
	v_mov_b32_e32 v142, v44
	s_waitcnt vmcnt(19)
	v_mov_b32_e32 v143, v28
	s_waitcnt lgkmcnt(0)
	v_pk_mul_f32 v[94:95], v[94:95], v[142:143]
	s_nop 0
	v_add_f32_e32 v76, v94, v95
	v_lshlrev_b64 v[94:95], 9, v[96:97]
	v_lshl_add_u64 v[94:95], v[132:133], 0, v[94:95]
	v_add_co_u32_e32 v94, vcc, 0xffc07000, v94
	v_cvt_pk_bf16_f32 v76, v76, s0
	s_nop 0
	v_addc_co_u32_e32 v95, vcc, -1, v95, vcc
	global_store_short v[94:95], v76, off
.LBB0_787:
	s_or_b64 exec, exec, s[2:3]
	v_or_b32_e32 v171, 57, v96
	v_mul_f32_e32 v94, 0x3e16c740, v77
	s_waitcnt lgkmcnt(0)
	v_cvt_pk_bf16_f32 v95, v94, s0
	v_mad_i64_i32 v[76:77], s[2:3], v171, s15, v[134:135]
	global_store_short v[76:77], v95, off
	s_nop 1
	v_mov_b32_dpp v95, v94 row_ror:8 row_mask:0xf bank_mask:0xf
	s_and_saveexec_b64 s[2:3], s[0:1]
	s_cbranch_execz .LBB0_789
	s_waitcnt vmcnt(19)
	v_mov_b32_e32 v142, v45
	s_waitcnt vmcnt(18)
	v_mov_b32_e32 v143, v29
	s_waitcnt lgkmcnt(0)
	v_pk_mul_f32 v[94:95], v[94:95], v[142:143]
	s_nop 0
	v_add_f32_e32 v94, v94, v95
	v_cvt_pk_bf16_f32 v142, v94, s0
	v_lshlrev_b64 v[94:95], 9, v[96:97]
	v_lshl_add_u64 v[94:95], v[132:133], 0, v[94:95]
	v_add_co_u32_e32 v94, vcc, 0xffc08000, v94
	s_nop 1
	v_addc_co_u32_e32 v95, vcc, -1, v95, vcc
	global_store_short v[94:95], v142, off offset:-3584
.LBB0_789:
	s_or_b64 exec, exec, s[2:3]
	v_mul_f32_e32 v142, 0x3e16c740, v78
	s_nop 1
	v_mov_b32_dpp v143, v142 row_ror:8 row_mask:0xf bank_mask:0xf
	v_or_b32_e32 v173, 58, v96
	v_cvt_pk_bf16_f32 v78, v142, s0
	s_waitcnt lgkmcnt(1)
	v_mad_i64_i32 v[94:95], s[2:3], v173, s15, v[134:135]
	global_store_short v[94:95], v78, off
	s_and_saveexec_b64 s[2:3], s[0:1]
	s_cbranch_execz .LBB0_791
	s_waitcnt vmcnt(18)
	v_mov_b32_e32 v188, v46
	s_waitcnt vmcnt(17)
	v_mov_b32_e32 v189, v30
	s_waitcnt lgkmcnt(0)
	v_pk_mul_f32 v[142:143], v[142:143], v[188:189]
	s_nop 0
	v_add_f32_e32 v78, v142, v143
	v_lshlrev_b64 v[142:143], 9, v[96:97]
	v_lshl_add_u64 v[142:143], v[132:133], 0, v[142:143]
	v_add_co_u32_e32 v142, vcc, 0xffc08000, v142
	v_cvt_pk_bf16_f32 v78, v78, s0
	s_nop 0
	v_addc_co_u32_e32 v143, vcc, -1, v143, vcc
	global_store_short v[142:143], v78, off offset:-3072
.LBB0_791:
	s_or_b64 exec, exec, s[2:3]
	v_or_b32_e32 v194, 59, v96
	v_mul_f32_e32 v142, 0x3e16c740, v79
	s_waitcnt lgkmcnt(0)
	v_cvt_pk_bf16_f32 v143, v142, s0
	v_mad_i64_i32 v[78:79], s[2:3], v194, s15, v[134:135]
	global_store_short v[78:79], v143, off
	s_nop 1
	v_mov_b32_dpp v143, v142 row_ror:8 row_mask:0xf bank_mask:0xf
	s_and_saveexec_b64 s[2:3], s[0:1]
	s_cbranch_execz .LBB0_793
	s_waitcnt vmcnt(17)
	v_mov_b32_e32 v134, v47
	s_waitcnt vmcnt(16)
	v_mov_b32_e32 v135, v31
	s_waitcnt lgkmcnt(0)
	v_pk_mul_f32 v[134:135], v[142:143], v[134:135]
	s_nop 0
	v_add_f32_e32 v134, v134, v135
	v_cvt_pk_bf16_f32 v142, v134, s0
	v_lshlrev_b64 v[134:135], 9, v[96:97]
	v_lshl_add_u64 v[132:133], v[132:133], 0, v[134:135]
	v_add_co_u32_e32 v132, vcc, 0xffc08000, v132
	s_nop 1
	v_addc_co_u32_e32 v133, vcc, -1, v133, vcc
	global_store_short v[132:133], v142, off offset:-2560

.LBB0_795:
	s_or_b64 exec, exec, s[2:3]
	v_mul_f32_e32 v132, 0x3e16c740, v48
	s_nop 1
	v_mov_b32_dpp v133, v132 row_ror:8 row_mask:0xf bank_mask:0xf
	v_lshlrev_b32_sdwa v110, v250, sext(v110) dst_sel:DWORD dst_unused:UNUSED_PAD src0_sel:DWORD src1_sel:BYTE_0
	v_ashrrev_i32_e32 v111, 31, v110
	v_lshl_add_u64 v[110:111], v[110:111], 1, s[46:47]
	v_lshl_add_u64 v[110:111], v[110:111], 0, v[136:137]
	v_cvt_pk_bf16_f32 v48, v132, s0
	global_store_short v[104:105], v48, off offset:64
	s_and_saveexec_b64 s[2:3], s[0:1]
	s_cbranch_execz .LBB0_797
	s_waitcnt vmcnt(32)
	v_mov_b32_e32 v104, v32
	s_waitcnt vmcnt(31)
	v_mov_b32_e32 v105, v16
	s_waitcnt lgkmcnt(0)
	v_pk_mul_f32 v[104:105], v[132:133], v[104:105]
	s_nop 0
	v_add_f32_e32 v48, v104, v105
	v_lshlrev_b64 v[104:105], 9, v[96:97]
	v_lshl_add_u64 v[104:105], v[110:111], 0, v[104:105]
	v_add_co_u32_e32 v104, vcc, 0xffc00000, v104
	v_cvt_pk_bf16_f32 v48, v48, s0
	s_nop 0
	v_addc_co_u32_e32 v105, vcc, -1, v105, vcc
	global_store_short v[104:105], v48, off
.LBB0_797:
	s_or_b64 exec, exec, s[2:3]
	v_mul_f32_e32 v48, 0x3e16c740, v49
	v_cvt_pk_bf16_f32 v49, v48, s0
	global_store_short v[98:99], v49, off offset:64
	s_nop 1
	v_mov_b32_dpp v49, v48 row_ror:8 row_mask:0xf bank_mask:0xf
	s_and_saveexec_b64 s[2:3], s[0:1]
	s_cbranch_execz .LBB0_799
	s_waitcnt vmcnt(31)
	v_mov_b32_e32 v98, v33
	s_waitcnt vmcnt(30)
	v_mov_b32_e32 v99, v17
	s_waitcnt lgkmcnt(0)
	v_pk_mul_f32 v[48:49], v[48:49], v[98:99]
	s_nop 0
	v_add_f32_e32 v48, v48, v49
	v_cvt_pk_bf16_f32 v98, v48, s0
	v_lshlrev_b64 v[48:49], 9, v[96:97]
	v_lshl_add_u64 v[48:49], v[110:111], 0, v[48:49]
	v_add_co_u32_e32 v48, vcc, 0xffc01000, v48
	s_nop 1
	v_addc_co_u32_e32 v49, vcc, -1, v49, vcc
	global_store_short v[48:49], v98, off offset:-3584
.LBB0_799:
	s_or_b64 exec, exec, s[2:3]
	v_mul_f32_e32 v48, 0x3e16c740, v50
	s_waitcnt lgkmcnt(0)
	v_cvt_pk_bf16_f32 v49, v48, s0
	global_store_short v[100:101], v49, off offset:64
	s_nop 1
	v_mov_b32_dpp v49, v48 row_ror:8 row_mask:0xf bank_mask:0xf
	s_and_saveexec_b64 s[2:3], s[0:1]
	s_cbranch_execz .LBB0_801
	s_waitcnt vmcnt(30)
	v_mov_b32_e32 v98, v34
	s_waitcnt vmcnt(29)
	v_mov_b32_e32 v99, v18
	s_waitcnt lgkmcnt(0)
	v_pk_mul_f32 v[48:49], v[48:49], v[98:99]
	s_nop 0
	v_add_f32_e32 v48, v48, v49
	v_cvt_pk_bf16_f32 v50, v48, s0
	v_lshlrev_b64 v[48:49], 9, v[96:97]
	v_lshl_add_u64 v[48:49], v[110:111], 0, v[48:49]
	v_add_co_u32_e32 v48, vcc, 0xffc01000, v48
	s_nop 1
	v_addc_co_u32_e32 v49, vcc, -1, v49, vcc
	global_store_short v[48:49], v50, off offset:-3072
.LBB0_801:
	s_or_b64 exec, exec, s[2:3]
	v_mul_f32_e32 v48, 0x3e16c740, v51
	s_waitcnt lgkmcnt(0)
	v_cvt_pk_bf16_f32 v49, v48, s0
	global_store_short v[102:103], v49, off offset:64
	s_nop 1
	v_mov_b32_dpp v49, v48 row_ror:8 row_mask:0xf bank_mask:0xf
	s_and_saveexec_b64 s[2:3], s[0:1]
	s_cbranch_execz .LBB0_803
	s_waitcnt vmcnt(29)
	v_mov_b32_e32 v50, v35
	s_waitcnt vmcnt(28)
	v_mov_b32_e32 v51, v19
	s_waitcnt lgkmcnt(0)
	v_pk_mul_f32 v[48:49], v[48:49], v[50:51]
	s_nop 0
	v_add_f32_e32 v48, v48, v49
	v_cvt_pk_bf16_f32 v50, v48, s0
	v_lshlrev_b64 v[48:49], 9, v[96:97]
	v_lshl_add_u64 v[48:49], v[110:111], 0, v[48:49]
	v_add_co_u32_e32 v48, vcc, 0xffc01000, v48
	s_nop 1
	v_addc_co_u32_e32 v49, vcc, -1, v49, vcc
	global_store_short v[48:49], v50, off offset:-2560
.LBB0_803:
	s_or_b64 exec, exec, s[2:3]
	v_mul_f32_e32 v48, 0x3e16c740, v52
	s_waitcnt lgkmcnt(0)
	v_cvt_pk_bf16_f32 v49, v48, s0
	global_store_short v[106:107], v49, off offset:64
	s_nop 1
	v_mov_b32_dpp v49, v48 row_ror:8 row_mask:0xf bank_mask:0xf
	s_and_saveexec_b64 s[2:3], s[0:1]
	s_cbranch_execz .LBB0_805
	s_waitcnt vmcnt(28)
	v_mov_b32_e32 v50, v36
	s_waitcnt vmcnt(27)
	v_mov_b32_e32 v51, v20
	s_waitcnt lgkmcnt(0)
	v_pk_mul_f32 v[48:49], v[48:49], v[50:51]
	s_nop 0
	v_add_f32_e32 v48, v48, v49
	v_cvt_pk_bf16_f32 v50, v48, s0
	v_lshlrev_b64 v[48:49], 9, v[96:97]
	v_lshl_add_u64 v[48:49], v[110:111], 0, v[48:49]
	v_add_co_u32_e32 v48, vcc, 0xffc01000, v48
	s_nop 1
	v_addc_co_u32_e32 v49, vcc, -1, v49, vcc
	global_store_short v[48:49], v50, off
.LBB0_805:
	s_or_b64 exec, exec, s[2:3]
	v_mul_f32_e32 v48, 0x3e16c740, v53
	s_waitcnt lgkmcnt(0)
	v_cvt_pk_bf16_f32 v49, v48, s0
	global_store_short v[108:109], v49, off offset:64
	s_nop 1
	v_mov_b32_dpp v49, v48 row_ror:8 row_mask:0xf bank_mask:0xf
	s_and_saveexec_b64 s[2:3], s[0:1]
	s_cbranch_execz .LBB0_807
	s_waitcnt vmcnt(27)
	v_mov_b32_e32 v50, v37
	s_waitcnt vmcnt(26)
	v_mov_b32_e32 v51, v21
	s_waitcnt lgkmcnt(0)
	v_pk_mul_f32 v[48:49], v[48:49], v[50:51]
	s_nop 0
	v_add_f32_e32 v48, v48, v49
	v_cvt_pk_bf16_f32 v50, v48, s0
	v_lshlrev_b64 v[48:49], 9, v[96:97]
	v_lshl_add_u64 v[48:49], v[110:111], 0, v[48:49]
	v_add_co_u32_e32 v48, vcc, 0xffc02000, v48
	s_nop 1
	v_addc_co_u32_e32 v49, vcc, -1, v49, vcc
	global_store_short v[48:49], v50, off offset:-3584
.LBB0_807:
	s_or_b64 exec, exec, s[2:3]
	v_mul_f32_e32 v48, 0x3e16c740, v54
	s_waitcnt lgkmcnt(0)
	v_cvt_pk_bf16_f32 v49, v48, s0
	global_store_short v[112:113], v49, off offset:64
	s_nop 1
	v_mov_b32_dpp v49, v48 row_ror:8 row_mask:0xf bank_mask:0xf
	s_and_saveexec_b64 s[2:3], s[0:1]
	s_cbranch_execz .LBB0_809
	s_waitcnt vmcnt(26)
	v_mov_b32_e32 v50, v38
	s_waitcnt vmcnt(25)
	v_mov_b32_e32 v51, v22
	s_waitcnt lgkmcnt(0)
	v_pk_mul_f32 v[48:49], v[48:49], v[50:51]
	s_nop 0
	v_add_f32_e32 v48, v48, v49
	v_cvt_pk_bf16_f32 v50, v48, s0
	v_lshlrev_b64 v[48:49], 9, v[96:97]
	v_lshl_add_u64 v[48:49], v[110:111], 0, v[48:49]
	v_add_co_u32_e32 v48, vcc, 0xffc02000, v48
	s_nop 1
	v_addc_co_u32_e32 v49, vcc, -1, v49, vcc
	global_store_short v[48:49], v50, off offset:-3072
.LBB0_809:
	s_or_b64 exec, exec, s[2:3]
	v_mul_f32_e32 v48, 0x3e16c740, v55
	s_waitcnt lgkmcnt(0)
	v_cvt_pk_bf16_f32 v49, v48, s0
	global_store_short v[114:115], v49, off offset:64
	s_nop 1
	v_mov_b32_dpp v49, v48 row_ror:8 row_mask:0xf bank_mask:0xf
	s_and_saveexec_b64 s[2:3], s[0:1]
	s_cbranch_execz .LBB0_811
	s_waitcnt vmcnt(25)
	v_mov_b32_e32 v50, v39
	s_waitcnt vmcnt(24)
	v_mov_b32_e32 v51, v23
	s_waitcnt lgkmcnt(0)
	v_pk_mul_f32 v[48:49], v[48:49], v[50:51]
	s_nop 0
	v_add_f32_e32 v48, v48, v49
	v_cvt_pk_bf16_f32 v50, v48, s0
	v_lshlrev_b64 v[48:49], 9, v[96:97]
	v_lshl_add_u64 v[48:49], v[110:111], 0, v[48:49]
	v_add_co_u32_e32 v48, vcc, 0xffc02000, v48
	s_nop 1
	v_addc_co_u32_e32 v49, vcc, -1, v49, vcc
	global_store_short v[48:49], v50, off offset:-2560
.LBB0_811:
	s_or_b64 exec, exec, s[2:3]
	v_mul_f32_e32 v48, 0x3e16c740, v56
	s_waitcnt lgkmcnt(0)
	v_cvt_pk_bf16_f32 v49, v48, s0
	global_store_short v[116:117], v49, off offset:64
	s_nop 1
	v_mov_b32_dpp v49, v48 row_ror:8 row_mask:0xf bank_mask:0xf
	s_and_saveexec_b64 s[2:3], s[0:1]
	s_cbranch_execz .LBB0_813
	s_waitcnt vmcnt(24)
	v_mov_b32_e32 v50, v40
	s_waitcnt vmcnt(23)
	v_mov_b32_e32 v51, v24
	s_waitcnt lgkmcnt(0)
	v_pk_mul_f32 v[48:49], v[48:49], v[50:51]
	s_nop 0
	v_add_f32_e32 v48, v48, v49
	v_cvt_pk_bf16_f32 v50, v48, s0
	v_lshlrev_b64 v[48:49], 9, v[96:97]
	v_lshl_add_u64 v[48:49], v[110:111], 0, v[48:49]
	v_add_co_u32_e32 v48, vcc, 0xffc02000, v48
	s_nop 1
	v_addc_co_u32_e32 v49, vcc, -1, v49, vcc
	global_store_short v[48:49], v50, off
.LBB0_813:
	s_or_b64 exec, exec, s[2:3]
	v_mul_f32_e32 v48, 0x3e16c740, v57
	s_waitcnt lgkmcnt(0)
	v_cvt_pk_bf16_f32 v49, v48, s0
	global_store_short v[118:119], v49, off offset:64
	s_nop 1
	v_mov_b32_dpp v49, v48 row_ror:8 row_mask:0xf bank_mask:0xf
	s_and_saveexec_b64 s[2:3], s[0:1]
	s_cbranch_execz .LBB0_815
	s_waitcnt vmcnt(23)
	v_mov_b32_e32 v50, v41
	s_waitcnt vmcnt(22)
	v_mov_b32_e32 v51, v25
	s_waitcnt lgkmcnt(0)
	v_pk_mul_f32 v[48:49], v[48:49], v[50:51]
	s_nop 0
	v_add_f32_e32 v48, v48, v49
	v_cvt_pk_bf16_f32 v50, v48, s0
	v_lshlrev_b64 v[48:49], 9, v[96:97]
	v_lshl_add_u64 v[48:49], v[110:111], 0, v[48:49]
	v_add_co_u32_e32 v48, vcc, 0xffc03000, v48
	s_nop 1
	v_addc_co_u32_e32 v49, vcc, -1, v49, vcc
	global_store_short v[48:49], v50, off offset:-3584
.LBB0_815:
	s_or_b64 exec, exec, s[2:3]
	v_mul_f32_e32 v48, 0x3e16c740, v58
	s_waitcnt lgkmcnt(0)
	v_cvt_pk_bf16_f32 v49, v48, s0
	global_store_short v[120:121], v49, off offset:64
	s_nop 1
	v_mov_b32_dpp v49, v48 row_ror:8 row_mask:0xf bank_mask:0xf
	s_and_saveexec_b64 s[2:3], s[0:1]
	s_cbranch_execz .LBB0_817
	s_waitcnt vmcnt(22)
	v_mov_b32_e32 v50, v42
	s_waitcnt vmcnt(21)
	v_mov_b32_e32 v51, v26
	s_waitcnt lgkmcnt(0)
	v_pk_mul_f32 v[48:49], v[48:49], v[50:51]
	s_nop 0
	v_add_f32_e32 v48, v48, v49
	v_cvt_pk_bf16_f32 v50, v48, s0
	v_lshlrev_b64 v[48:49], 9, v[96:97]
	v_lshl_add_u64 v[48:49], v[110:111], 0, v[48:49]
	v_add_co_u32_e32 v48, vcc, 0xffc03000, v48
	s_nop 1
	v_addc_co_u32_e32 v49, vcc, -1, v49, vcc
	global_store_short v[48:49], v50, off offset:-3072
.LBB0_817:
	s_or_b64 exec, exec, s[2:3]
	v_mul_f32_e32 v48, 0x3e16c740, v59
	s_waitcnt lgkmcnt(0)
	v_cvt_pk_bf16_f32 v49, v48, s0
	global_store_short v[122:123], v49, off offset:64
	s_nop 1
	v_mov_b32_dpp v49, v48 row_ror:8 row_mask:0xf bank_mask:0xf
	s_and_saveexec_b64 s[2:3], s[0:1]
	s_cbranch_execz .LBB0_819
	s_waitcnt vmcnt(21)
	v_mov_b32_e32 v50, v43
	s_waitcnt vmcnt(20)
	v_mov_b32_e32 v51, v27
	s_waitcnt lgkmcnt(0)
	v_pk_mul_f32 v[48:49], v[48:49], v[50:51]
	s_nop 0
	v_add_f32_e32 v48, v48, v49
	v_cvt_pk_bf16_f32 v50, v48, s0
	v_lshlrev_b64 v[48:49], 9, v[96:97]
	v_lshl_add_u64 v[48:49], v[110:111], 0, v[48:49]
	v_add_co_u32_e32 v48, vcc, 0xffc03000, v48
	s_nop 1
	v_addc_co_u32_e32 v49, vcc, -1, v49, vcc
	global_store_short v[48:49], v50, off offset:-2560
.LBB0_819:
	s_or_b64 exec, exec, s[2:3]
	v_mul_f32_e32 v48, 0x3e16c740, v60
	s_waitcnt lgkmcnt(0)
	v_cvt_pk_bf16_f32 v49, v48, s0
	global_store_short v[124:125], v49, off offset:64
	s_nop 1
	v_mov_b32_dpp v49, v48 row_ror:8 row_mask:0xf bank_mask:0xf
	s_and_saveexec_b64 s[2:3], s[0:1]
	s_cbranch_execz .LBB0_821
	s_waitcnt vmcnt(20)
	v_mov_b32_e32 v50, v44
	s_waitcnt vmcnt(19)
	v_mov_b32_e32 v51, v28
	s_waitcnt lgkmcnt(0)
	v_pk_mul_f32 v[48:49], v[48:49], v[50:51]
	s_nop 0
	v_add_f32_e32 v48, v48, v49
	v_cvt_pk_bf16_f32 v50, v48, s0
	v_lshlrev_b64 v[48:49], 9, v[96:97]
	v_lshl_add_u64 v[48:49], v[110:111], 0, v[48:49]
	v_add_co_u32_e32 v48, vcc, 0xffc03000, v48
	s_nop 1
	v_addc_co_u32_e32 v49, vcc, -1, v49, vcc
	global_store_short v[48:49], v50, off
.LBB0_821:
	s_or_b64 exec, exec, s[2:3]
	v_mul_f32_e32 v48, 0x3e16c740, v61
	s_waitcnt lgkmcnt(0)
	v_cvt_pk_bf16_f32 v49, v48, s0
	global_store_short v[126:127], v49, off offset:64
	s_nop 1
	v_mov_b32_dpp v49, v48 row_ror:8 row_mask:0xf bank_mask:0xf
	s_and_saveexec_b64 s[2:3], s[0:1]
	s_cbranch_execz .LBB0_823
	s_waitcnt vmcnt(19)
	v_mov_b32_e32 v50, v45
	s_waitcnt vmcnt(18)
	v_mov_b32_e32 v51, v29
	s_waitcnt lgkmcnt(0)
	v_pk_mul_f32 v[48:49], v[48:49], v[50:51]
	s_nop 0
	v_add_f32_e32 v48, v48, v49
	v_cvt_pk_bf16_f32 v50, v48, s0
	v_lshlrev_b64 v[48:49], 9, v[96:97]
	v_lshl_add_u64 v[48:49], v[110:111], 0, v[48:49]
	v_add_co_u32_e32 v48, vcc, 0xffc04000, v48
	s_nop 1
	v_addc_co_u32_e32 v49, vcc, -1, v49, vcc
	global_store_short v[48:49], v50, off offset:-3584
.LBB0_823:
	s_or_b64 exec, exec, s[2:3]
	v_mul_f32_e32 v48, 0x3e16c740, v62
	s_waitcnt lgkmcnt(0)
	v_cvt_pk_bf16_f32 v49, v48, s0
	global_store_short v[128:129], v49, off offset:64
	s_nop 1
	v_mov_b32_dpp v49, v48 row_ror:8 row_mask:0xf bank_mask:0xf
	s_and_saveexec_b64 s[2:3], s[0:1]
	s_cbranch_execz .LBB0_825
	s_waitcnt vmcnt(18)
	v_mov_b32_e32 v50, v46
	s_waitcnt vmcnt(17)
	v_mov_b32_e32 v51, v30
	s_waitcnt lgkmcnt(0)
	v_pk_mul_f32 v[48:49], v[48:49], v[50:51]
	s_nop 0
	v_add_f32_e32 v48, v48, v49
	v_cvt_pk_bf16_f32 v50, v48, s0
	v_lshlrev_b64 v[48:49], 9, v[96:97]
	v_lshl_add_u64 v[48:49], v[110:111], 0, v[48:49]
	v_add_co_u32_e32 v48, vcc, 0xffc04000, v48
	s_nop 1
	v_addc_co_u32_e32 v49, vcc, -1, v49, vcc
	global_store_short v[48:49], v50, off offset:-3072
.LBB0_825:
	s_or_b64 exec, exec, s[2:3]
	v_mul_f32_e32 v48, 0x3e16c740, v63
	s_waitcnt lgkmcnt(0)
	v_cvt_pk_bf16_f32 v49, v48, s0
	global_store_short v[130:131], v49, off offset:64
	s_nop 1
	v_mov_b32_dpp v49, v48 row_ror:8 row_mask:0xf bank_mask:0xf
	s_and_saveexec_b64 s[2:3], s[0:1]
	s_cbranch_execz .LBB0_827
	s_waitcnt vmcnt(17)
	v_mov_b32_e32 v30, v47
	s_waitcnt vmcnt(16) lgkmcnt(0)
	v_pk_mul_f32 v[16:17], v[48:49], v[30:31]
	s_mov_b32 s22, 0x1fca0
	v_add_f32_e32 v16, v16, v17
	v_cvt_pk_bf16_f32 v18, v16, s0
	v_lshlrev_b64 v[16:17], 9, v[96:97]
	v_lshl_add_u64 v[16:17], v[110:111], 0, v[16:17]
	v_add_co_u32_e32 v16, vcc, 0xffc04000, v16
	v_lshlrev_b32_e32 v19, 5, v153
	s_nop 0
	v_addc_co_u32_e32 v17, vcc, -1, v17, vcc
	global_store_short v[16:17], v18, off offset:-2560
	v_lshlrev_b32_e32 v17, 5, v149
	v_and_or_b32 v17, v17, s22, v145
	v_lshlrev_b32_e32 v18, 5, v151
	s_mov_b32 s22, 0x1fcc0
	v_and_or_b32 v18, v18, s22, v145
	s_mov_b32 s22, 0x1fce0
	v_and_or_b32 v19, v19, s22, v145
	v_lshlrev_b32_e32 v20, 5, v154
	s_mov_b32 s22, 0x1fd80
	v_and_or_b32 v20, v20, s22, v145
	v_lshlrev_b32_e32 v21, 5, v156
	s_mov_b32 s22, 0x1fda0
	v_and_or_b32 v21, v21, s22, v145
	v_lshlrev_b32_e32 v22, 5, v158
	s_mov_b32 s22, 0x1fdc0
	v_and_or_b32 v22, v22, s22, v145
	v_lshlrev_b32_e32 v23, 5, v160
	s_mov_b32 s22, 0x1fde0
	v_and_or_b32 v23, v23, s22, v145
	v_lshlrev_b32_e32 v24, 5, v162
	s_mov_b32 s22, 0x1fe80
	v_lshlrev_b32_e32 v28, 5, v169
	s_mov_b32 s15, 0x1ff80
	v_and_or_b32 v24, v24, s22, v145
	v_lshlrev_b32_e32 v25, 5, v164
	s_mov_b32 s22, 0x1fea0
	v_and_or_b32 v28, v28, s15, v145
	v_lshlrev_b32_e32 v29, 5, v171
	s_mov_b32 s15, 0x1ffa0
	v_and_or_b32 v25, v25, s22, v145
	v_lshlrev_b32_e32 v26, 5, v166
	s_mov_b32 s22, 0x1fec0
	v_and_or_b32 v29, v29, s15, v145
	v_lshlrev_b32_e32 v30, 5, v173
	s_mov_b32 s15, 0x1ffc0
	v_and_or_b32 v26, v26, s22, v145
	v_lshlrev_b32_e32 v27, 5, v167
	s_mov_b32 s22, 0x1fee0
	v_and_or_b32 v30, v30, s15, v145
	v_lshlrev_b32_e32 v31, 5, v194
	s_mov_b32 s15, 0x1ffe0
	v_and_or_b32 v27, v27, s22, v145
	v_and_or_b32 v31, v31, s15, v145
	v_lshlrev_b32_e32 v16, 2, v147
	v_lshlrev_b32_e32 v17, 2, v17
	v_lshlrev_b32_e32 v18, 2, v18
	v_lshlrev_b32_e32 v19, 2, v19
	v_lshlrev_b32_e32 v20, 2, v20
	v_lshlrev_b32_e32 v21, 2, v21
	v_lshlrev_b32_e32 v22, 2, v22
	v_lshlrev_b32_e32 v23, 2, v23
	v_lshlrev_b32_e32 v24, 2, v24
	v_lshlrev_b32_e32 v25, 2, v25
	v_lshlrev_b32_e32 v26, 2, v26
	v_lshlrev_b32_e32 v27, 2, v27
	v_lshlrev_b32_e32 v28, 2, v28
	v_lshlrev_b32_e32 v29, 2, v29
	v_lshlrev_b32_e32 v30, 2, v30
	v_lshlrev_b32_e32 v31, 2, v31
	global_load_dword v32, v16, s[8:9]
	s_nop 0
	global_load_dword v16, v16, s[10:11]
	s_nop 0
	global_load_dword v33, v17, s[8:9]
	s_nop 0
	global_load_dword v17, v17, s[10:11]
	s_nop 0
	global_load_dword v34, v18, s[8:9]
	s_nop 0
	global_load_dword v18, v18, s[10:11]
	s_nop 0
	global_load_dword v35, v19, s[8:9]
	s_nop 0
	global_load_dword v19, v19, s[10:11]
	s_nop 0
	global_load_dword v36, v20, s[8:9]
	s_nop 0
	global_load_dword v20, v20, s[10:11]
	s_nop 0
	global_load_dword v37, v21, s[8:9]
	s_nop 0
	global_load_dword v21, v21, s[10:11]
	s_nop 0
	global_load_dword v38, v22, s[8:9]
	s_nop 0
	global_load_dword v22, v22, s[10:11]
	s_nop 0
	global_load_dword v39, v23, s[8:9]
	s_nop 0
	global_load_dword v23, v23, s[10:11]
	s_nop 0
	global_load_dword v40, v24, s[8:9]
	s_nop 0
	global_load_dword v24, v24, s[10:11]
	s_nop 0
	global_load_dword v41, v25, s[8:9]
	s_nop 0
	global_load_dword v25, v25, s[10:11]
	s_nop 0
	global_load_dword v42, v26, s[8:9]
	s_nop 0
	global_load_dword v26, v26, s[10:11]
	s_nop 0
	global_load_dword v43, v27, s[8:9]
	s_nop 0
	global_load_dword v27, v27, s[10:11]
	s_nop 0
	global_load_dword v44, v28, s[8:9]
	s_nop 0
	global_load_dword v28, v28, s[10:11]
	s_nop 0
	global_load_dword v45, v29, s[8:9]
	s_nop 0
	global_load_dword v29, v29, s[10:11]
	s_nop 0
	global_load_dword v46, v30, s[8:9]
	s_nop 0
	global_load_dword v30, v30, s[10:11]
	s_nop 0
	global_load_dword v47, v31, s[8:9]
	s_nop 0
	global_load_dword v31, v31, s[10:11]
.LBB0_827:
	s_or_b64 exec, exec, s[2:3]
	v_mul_f32_e32 v48, 0x3e16c740, v0
	s_waitcnt lgkmcnt(0)
	s_nop 1
	v_mov_b32_dpp v49, v48 row_ror:8 row_mask:0xf bank_mask:0xf
	v_cvt_pk_bf16_f32 v0, v48, s0
	global_store_short v[80:81], v0, off offset:64
	s_and_saveexec_b64 s[2:3], s[0:1]
	s_cbranch_execz .LBB0_829
	s_waitcnt vmcnt(32)
	v_mov_b32_e32 v50, v32
	s_waitcnt vmcnt(31)
	v_mov_b32_e32 v51, v16
	s_waitcnt lgkmcnt(0)
	v_pk_mul_f32 v[48:49], v[48:49], v[50:51]
	s_nop 0
	v_add_f32_e32 v0, v48, v49
	v_lshlrev_b64 v[48:49], 9, v[96:97]
	v_lshl_add_u64 v[48:49], v[110:111], 0, v[48:49]
	v_add_co_u32_e32 v48, vcc, 0xffc04000, v48
	v_cvt_pk_bf16_f32 v0, v0, s0
	s_nop 0
	v_addc_co_u32_e32 v49, vcc, -1, v49, vcc
	global_store_short v[48:49], v0, off
.LBB0_829:
	s_or_b64 exec, exec, s[2:3]
	v_mul_f32_e32 v0, 0x3e16c740, v1
	v_cvt_pk_bf16_f32 v1, v0, s0
	global_store_short v[64:65], v1, off offset:64
	s_nop 1
	v_mov_b32_dpp v1, v0 row_ror:8 row_mask:0xf bank_mask:0xf
	s_and_saveexec_b64 s[2:3], s[0:1]
	s_cbranch_execz .LBB0_831
	s_waitcnt vmcnt(31)
	v_mov_b32_e32 v16, v33
	s_waitcnt vmcnt(30) lgkmcnt(0)
	v_pk_mul_f32 v[0:1], v[0:1], v[16:17]
	s_nop 0
	v_add_f32_e32 v0, v0, v1
	v_cvt_pk_bf16_f32 v16, v0, s0
	v_lshlrev_b64 v[0:1], 9, v[96:97]
	v_lshl_add_u64 v[0:1], v[110:111], 0, v[0:1]
	v_add_co_u32_e32 v0, vcc, 0xffc05000, v0
	s_nop 1
	v_addc_co_u32_e32 v1, vcc, -1, v1, vcc
	global_store_short v[0:1], v16, off offset:-3584
.LBB0_831:
	s_or_b64 exec, exec, s[2:3]
	v_mul_f32_e32 v0, 0x3e16c740, v2
	s_waitcnt lgkmcnt(0)
	v_cvt_pk_bf16_f32 v1, v0, s0
	global_store_short v[82:83], v1, off offset:64
	s_nop 1
	v_mov_b32_dpp v1, v0 row_ror:8 row_mask:0xf bank_mask:0xf
	s_and_saveexec_b64 s[2:3], s[0:1]
	s_cbranch_execz .LBB0_833
	s_waitcnt vmcnt(30)
	v_mov_b32_e32 v16, v34
	s_waitcnt vmcnt(29)
	v_mov_b32_e32 v17, v18
	s_waitcnt lgkmcnt(0)
	v_pk_mul_f32 v[0:1], v[0:1], v[16:17]
	s_nop 0
	v_add_f32_e32 v0, v0, v1
	v_cvt_pk_bf16_f32 v2, v0, s0
	v_lshlrev_b64 v[0:1], 9, v[96:97]
	v_lshl_add_u64 v[0:1], v[110:111], 0, v[0:1]
	v_add_co_u32_e32 v0, vcc, 0xffc05000, v0
	s_nop 1
	v_addc_co_u32_e32 v1, vcc, -1, v1, vcc
	global_store_short v[0:1], v2, off offset:-3072
.LBB0_833:
	s_or_b64 exec, exec, s[2:3]
	v_mul_f32_e32 v0, 0x3e16c740, v3
	s_waitcnt lgkmcnt(0)
	v_cvt_pk_bf16_f32 v1, v0, s0
	global_store_short v[66:67], v1, off offset:64
	s_nop 1
	v_mov_b32_dpp v1, v0 row_ror:8 row_mask:0xf bank_mask:0xf
	s_and_saveexec_b64 s[2:3], s[0:1]
	s_cbranch_execz .LBB0_835
	s_waitcnt vmcnt(29)
	v_mov_b32_e32 v18, v35
	s_waitcnt vmcnt(28) lgkmcnt(0)
	v_pk_mul_f32 v[0:1], v[0:1], v[18:19]
	s_nop 0
	v_add_f32_e32 v0, v0, v1
	v_cvt_pk_bf16_f32 v2, v0, s0
	v_lshlrev_b64 v[0:1], 9, v[96:97]
	v_lshl_add_u64 v[0:1], v[110:111], 0, v[0:1]
	v_add_co_u32_e32 v0, vcc, 0xffc05000, v0
	s_nop 1
	v_addc_co_u32_e32 v1, vcc, -1, v1, vcc
	global_store_short v[0:1], v2, off offset:-2560
.LBB0_835:
	s_or_b64 exec, exec, s[2:3]
	v_mul_f32_e32 v0, 0x3e16c740, v4
	s_waitcnt lgkmcnt(0)
	v_cvt_pk_bf16_f32 v1, v0, s0
	global_store_short v[84:85], v1, off offset:64
	s_nop 1
	v_mov_b32_dpp v1, v0 row_ror:8 row_mask:0xf bank_mask:0xf
	s_and_saveexec_b64 s[2:3], s[0:1]
	s_cbranch_execz .LBB0_837
	s_waitcnt vmcnt(28)
	v_mov_b32_e32 v2, v36
	s_waitcnt vmcnt(27)
	v_mov_b32_e32 v3, v20
	s_waitcnt lgkmcnt(0)
	v_pk_mul_f32 v[0:1], v[0:1], v[2:3]
	s_nop 0
	v_add_f32_e32 v0, v0, v1
	v_cvt_pk_bf16_f32 v2, v0, s0
	v_lshlrev_b64 v[0:1], 9, v[96:97]
	v_lshl_add_u64 v[0:1], v[110:111], 0, v[0:1]
	v_add_co_u32_e32 v0, vcc, 0xffc05000, v0
	s_nop 1
	v_addc_co_u32_e32 v1, vcc, -1, v1, vcc
	global_store_short v[0:1], v2, off
.LBB0_837:
	s_or_b64 exec, exec, s[2:3]
	v_mul_f32_e32 v0, 0x3e16c740, v5
	s_waitcnt lgkmcnt(0)
	v_cvt_pk_bf16_f32 v1, v0, s0
	global_store_short v[68:69], v1, off offset:64
	s_nop 1
	v_mov_b32_dpp v1, v0 row_ror:8 row_mask:0xf bank_mask:0xf
	s_and_saveexec_b64 s[2:3], s[0:1]
	s_cbranch_execz .LBB0_839
	s_waitcnt vmcnt(27)
	v_mov_b32_e32 v20, v37
	s_waitcnt vmcnt(26) lgkmcnt(0)
	v_pk_mul_f32 v[0:1], v[0:1], v[20:21]
	s_nop 0
	v_add_f32_e32 v0, v0, v1
	v_cvt_pk_bf16_f32 v2, v0, s0
	v_lshlrev_b64 v[0:1], 9, v[96:97]
	v_lshl_add_u64 v[0:1], v[110:111], 0, v[0:1]
	v_add_co_u32_e32 v0, vcc, 0xffc06000, v0
	s_nop 1
	v_addc_co_u32_e32 v1, vcc, -1, v1, vcc
	global_store_short v[0:1], v2, off offset:-3584
.LBB0_839:
	s_or_b64 exec, exec, s[2:3]
	v_mul_f32_e32 v0, 0x3e16c740, v6
	s_waitcnt lgkmcnt(0)
	v_cvt_pk_bf16_f32 v1, v0, s0
	global_store_short v[86:87], v1, off offset:64
	s_nop 1
	v_mov_b32_dpp v1, v0 row_ror:8 row_mask:0xf bank_mask:0xf
	s_and_saveexec_b64 s[2:3], s[0:1]
	s_cbranch_execz .LBB0_841
	s_waitcnt vmcnt(26)
	v_mov_b32_e32 v2, v38
	s_waitcnt vmcnt(25)
	v_mov_b32_e32 v3, v22
	s_waitcnt lgkmcnt(0)
	v_pk_mul_f32 v[0:1], v[0:1], v[2:3]
	s_nop 0
	v_add_f32_e32 v0, v0, v1
	v_cvt_pk_bf16_f32 v2, v0, s0
	v_lshlrev_b64 v[0:1], 9, v[96:97]
	v_lshl_add_u64 v[0:1], v[110:111], 0, v[0:1]
	v_add_co_u32_e32 v0, vcc, 0xffc06000, v0
	s_nop 1
	v_addc_co_u32_e32 v1, vcc, -1, v1, vcc
	global_store_short v[0:1], v2, off offset:-3072
.LBB0_841:
	s_or_b64 exec, exec, s[2:3]
	v_mul_f32_e32 v0, 0x3e16c740, v7
	s_waitcnt lgkmcnt(0)
	v_cvt_pk_bf16_f32 v1, v0, s0
	global_store_short v[70:71], v1, off offset:64
	s_nop 1
	v_mov_b32_dpp v1, v0 row_ror:8 row_mask:0xf bank_mask:0xf
	s_and_saveexec_b64 s[2:3], s[0:1]
	s_cbranch_execz .LBB0_843
	s_waitcnt vmcnt(25)
	v_mov_b32_e32 v22, v39
	s_waitcnt vmcnt(24) lgkmcnt(0)
	v_pk_mul_f32 v[0:1], v[0:1], v[22:23]
	s_nop 0
	v_add_f32_e32 v0, v0, v1
	v_cvt_pk_bf16_f32 v2, v0, s0
	v_lshlrev_b64 v[0:1], 9, v[96:97]
	v_lshl_add_u64 v[0:1], v[110:111], 0, v[0:1]
	v_add_co_u32_e32 v0, vcc, 0xffc06000, v0
	s_nop 1
	v_addc_co_u32_e32 v1, vcc, -1, v1, vcc
	global_store_short v[0:1], v2, off offset:-2560
.LBB0_843:
	s_or_b64 exec, exec, s[2:3]
	v_mul_f32_e32 v0, 0x3e16c740, v8
	s_waitcnt lgkmcnt(0)
	v_cvt_pk_bf16_f32 v1, v0, s0
	global_store_short v[88:89], v1, off offset:64
	s_nop 1
	v_mov_b32_dpp v1, v0 row_ror:8 row_mask:0xf bank_mask:0xf
	s_and_saveexec_b64 s[2:3], s[0:1]
	s_cbranch_execz .LBB0_845
	s_waitcnt vmcnt(24)
	v_mov_b32_e32 v2, v40
	s_waitcnt vmcnt(23)
	v_mov_b32_e32 v3, v24
	s_waitcnt lgkmcnt(0)
	v_pk_mul_f32 v[0:1], v[0:1], v[2:3]
	s_nop 0
	v_add_f32_e32 v0, v0, v1
	v_cvt_pk_bf16_f32 v2, v0, s0
	v_lshlrev_b64 v[0:1], 9, v[96:97]
	v_lshl_add_u64 v[0:1], v[110:111], 0, v[0:1]
	v_add_co_u32_e32 v0, vcc, 0xffc06000, v0
	s_nop 1
	v_addc_co_u32_e32 v1, vcc, -1, v1, vcc
	global_store_short v[0:1], v2, off
.LBB0_845:
	s_or_b64 exec, exec, s[2:3]
	v_mul_f32_e32 v0, 0x3e16c740, v9
	s_waitcnt lgkmcnt(0)
	v_cvt_pk_bf16_f32 v1, v0, s0
	global_store_short v[72:73], v1, off offset:64
	s_nop 1
	v_mov_b32_dpp v1, v0 row_ror:8 row_mask:0xf bank_mask:0xf
	s_and_saveexec_b64 s[2:3], s[0:1]
	s_cbranch_execz .LBB0_847
	s_waitcnt vmcnt(23)
	v_mov_b32_e32 v24, v41
	s_waitcnt vmcnt(22) lgkmcnt(0)
	v_pk_mul_f32 v[0:1], v[0:1], v[24:25]
	s_nop 0
	v_add_f32_e32 v0, v0, v1
	v_cvt_pk_bf16_f32 v2, v0, s0
	v_lshlrev_b64 v[0:1], 9, v[96:97]
	v_lshl_add_u64 v[0:1], v[110:111], 0, v[0:1]
	v_add_co_u32_e32 v0, vcc, 0xffc07000, v0
	s_nop 1
	v_addc_co_u32_e32 v1, vcc, -1, v1, vcc
	global_store_short v[0:1], v2, off offset:-3584
.LBB0_847:
	s_or_b64 exec, exec, s[2:3]
	v_mul_f32_e32 v0, 0x3e16c740, v10
	s_waitcnt lgkmcnt(0)
	v_cvt_pk_bf16_f32 v1, v0, s0
	global_store_short v[90:91], v1, off offset:64
	s_nop 1
	v_mov_b32_dpp v1, v0 row_ror:8 row_mask:0xf bank_mask:0xf
	s_and_saveexec_b64 s[2:3], s[0:1]
	s_cbranch_execz .LBB0_849
	s_waitcnt vmcnt(22)
	v_mov_b32_e32 v2, v42
	s_waitcnt vmcnt(21)
	v_mov_b32_e32 v3, v26
	s_waitcnt lgkmcnt(0)
	v_pk_mul_f32 v[0:1], v[0:1], v[2:3]
	s_nop 0
	v_add_f32_e32 v0, v0, v1
	v_cvt_pk_bf16_f32 v2, v0, s0
	v_lshlrev_b64 v[0:1], 9, v[96:97]
	v_lshl_add_u64 v[0:1], v[110:111], 0, v[0:1]
	v_add_co_u32_e32 v0, vcc, 0xffc07000, v0
	s_nop 1
	v_addc_co_u32_e32 v1, vcc, -1, v1, vcc
	global_store_short v[0:1], v2, off offset:-3072
.LBB0_849:
	s_or_b64 exec, exec, s[2:3]
	v_mul_f32_e32 v0, 0x3e16c740, v11
	s_waitcnt lgkmcnt(0)
	v_cvt_pk_bf16_f32 v1, v0, s0
	global_store_short v[74:75], v1, off offset:64
	s_nop 1
	v_mov_b32_dpp v1, v0 row_ror:8 row_mask:0xf bank_mask:0xf
	s_and_saveexec_b64 s[2:3], s[0:1]
	s_cbranch_execz .LBB0_851
	s_waitcnt vmcnt(21)
	v_mov_b32_e32 v26, v43
	s_waitcnt vmcnt(20) lgkmcnt(0)
	v_pk_mul_f32 v[0:1], v[0:1], v[26:27]
	s_nop 0
	v_add_f32_e32 v0, v0, v1
	v_cvt_pk_bf16_f32 v2, v0, s0
	v_lshlrev_b64 v[0:1], 9, v[96:97]
	v_lshl_add_u64 v[0:1], v[110:111], 0, v[0:1]
	v_add_co_u32_e32 v0, vcc, 0xffc07000, v0
	s_nop 1
	v_addc_co_u32_e32 v1, vcc, -1, v1, vcc
	global_store_short v[0:1], v2, off offset:-2560
.LBB0_851:
	s_or_b64 exec, exec, s[2:3]
	v_mul_f32_e32 v0, 0x3e16c740, v12
	s_waitcnt lgkmcnt(0)
	v_cvt_pk_bf16_f32 v1, v0, s0
	global_store_short v[92:93], v1, off offset:64
	s_nop 1
	v_mov_b32_dpp v1, v0 row_ror:8 row_mask:0xf bank_mask:0xf
	s_and_saveexec_b64 s[2:3], s[0:1]
	s_cbranch_execz .LBB0_853
	s_waitcnt vmcnt(20)
	v_mov_b32_e32 v2, v44
	s_waitcnt vmcnt(19)
	v_mov_b32_e32 v3, v28
	s_waitcnt lgkmcnt(0)
	v_pk_mul_f32 v[0:1], v[0:1], v[2:3]
	s_nop 0
	v_add_f32_e32 v0, v0, v1
	v_cvt_pk_bf16_f32 v2, v0, s0
	v_lshlrev_b64 v[0:1], 9, v[96:97]
	v_lshl_add_u64 v[0:1], v[110:111], 0, v[0:1]
	v_add_co_u32_e32 v0, vcc, 0xffc07000, v0
	s_nop 1
	v_addc_co_u32_e32 v1, vcc, -1, v1, vcc
	global_store_short v[0:1], v2, off
.LBB0_853:
	s_or_b64 exec, exec, s[2:3]
	v_mul_f32_e32 v0, 0x3e16c740, v13
	s_waitcnt lgkmcnt(0)
	v_cvt_pk_bf16_f32 v1, v0, s0
	global_store_short v[76:77], v1, off offset:64
	s_nop 1
	v_mov_b32_dpp v1, v0 row_ror:8 row_mask:0xf bank_mask:0xf
	s_and_saveexec_b64 s[2:3], s[0:1]
	s_cbranch_execz .LBB0_855
	s_waitcnt vmcnt(19)
	v_mov_b32_e32 v28, v45
	s_waitcnt vmcnt(18) lgkmcnt(0)
	v_pk_mul_f32 v[0:1], v[0:1], v[28:29]
	s_nop 0
	v_add_f32_e32 v0, v0, v1
	v_cvt_pk_bf16_f32 v2, v0, s0
	v_lshlrev_b64 v[0:1], 9, v[96:97]
	v_lshl_add_u64 v[0:1], v[110:111], 0, v[0:1]
	v_add_co_u32_e32 v0, vcc, 0xffc08000, v0
	s_nop 1
	v_addc_co_u32_e32 v1, vcc, -1, v1, vcc
	global_store_short v[0:1], v2, off offset:-3584
.LBB0_855:
	s_or_b64 exec, exec, s[2:3]
	v_mul_f32_e32 v0, 0x3e16c740, v14
	s_waitcnt lgkmcnt(0)
	v_cvt_pk_bf16_f32 v1, v0, s0
	global_store_short v[94:95], v1, off offset:64
	s_nop 1
	v_mov_b32_dpp v1, v0 row_ror:8 row_mask:0xf bank_mask:0xf
	s_and_saveexec_b64 s[2:3], s[0:1]
	s_cbranch_execz .LBB0_857
	s_waitcnt vmcnt(18)
	v_mov_b32_e32 v2, v46
	s_waitcnt vmcnt(17)
	v_mov_b32_e32 v3, v30
	s_waitcnt lgkmcnt(0)
	v_pk_mul_f32 v[0:1], v[0:1], v[2:3]
	s_nop 0
	v_add_f32_e32 v0, v0, v1
	v_cvt_pk_bf16_f32 v2, v0, s0
	v_lshlrev_b64 v[0:1], 9, v[96:97]
	v_lshl_add_u64 v[0:1], v[110:111], 0, v[0:1]
	v_add_co_u32_e32 v0, vcc, 0xffc08000, v0
	s_nop 1
	v_addc_co_u32_e32 v1, vcc, -1, v1, vcc
	global_store_short v[0:1], v2, off offset:-3072
.LBB0_857:
	s_or_b64 exec, exec, s[2:3]
	v_mul_f32_e32 v0, 0x3e16c740, v15
	s_waitcnt lgkmcnt(0)
	s_nop 1
	v_mov_b32_dpp v1, v0 row_ror:8 row_mask:0xf bank_mask:0xf
	v_cvt_pk_bf16_f32 v2, v0, s0
	global_store_short v[78:79], v2, off offset:64
	s_and_saveexec_b64 s[2:3], s[0:1]
	s_cbranch_execz .LBB0_708
	s_waitcnt vmcnt(17)
	v_mov_b32_e32 v30, v47
	s_waitcnt vmcnt(16) lgkmcnt(0)
	v_pk_mul_f32 v[0:1], v[0:1], v[30:31]
	s_nop 0
	v_add_f32_e32 v0, v0, v1
	v_cvt_pk_bf16_f32 v2, v0, s0
	v_lshlrev_b64 v[0:1], 9, v[96:97]
	v_lshl_add_u64 v[0:1], v[110:111], 0, v[0:1]
	v_add_co_u32_e32 v0, vcc, 0xffc08000, v0
	s_nop 1
	v_addc_co_u32_e32 v1, vcc, -1, v1, vcc
	global_store_short v[0:1], v2, off offset:-2560
	s_branch .LBB0_708
